# XCD-local grid barriers conservative set + guard: only when the grid is 256 blocks and the id->XCC remap succeeded
# speedup vs baseline: 1.0165x; 1.0026x over previous
; #define LAS __attribute__((address_space(3)))
; __device__ __forceinline__ unsigned xb_ld(unsigned* p)              { return __hip_atomic_load(p, __ATOMIC_RELAXED, __HIP_MEMORY_SCOPE_AGENT); }
; __device__ __forceinline__ unsigned xb_xcc_id() { return (unsigned)__builtin_amdgcn_s_getreg((3 << 11) | 20) & 0xFu; }
; __global__ void __launch_bounds__(NTHREADS) mega_kernel(Params p_) {
;     ...
;     if (F.G == 256) { F.r0 = F.xcd * SEQ + F.rank * NWAVES + F.wave; F.rstep = 256; F.rend = (F.xcd + 1) * SEQ; }
;     else { F.r0 = F.gw; F.rstep = F.NGW; F.rend = MTOK; }
;     ...
;         if (coop && ph + 1 < ph_hi) {
;             if (ph == 0) {
;                 cg::this_grid().sync();
;                 volatile LAS unsigned* st_ = (volatile LAS unsigned*)(F.lds + 131072 + 64);
;                 if (threadIdx.x == 0) {
;                     unsigned* bar_ = (unsigned*)F.ws; bool ok_ = (gridDim.x % 8u) == 0u;
;                     for (unsigned j = 0; j < 16; ++j) { const unsigned c_ = xb_ld(&bar_[XB_XCNT(j)]); ok_ = ok_ && (c_ == (j < 8u ? gridDim.x / 8u : 0u)); }
;                     const unsigned x_ = xb_xcc_id();
;                     st_[3] = (ok_ && x_ < 8u && st_[2] < gridDim.x / 8u) ? (st_[2] * 8u + x_) : blockIdx.x;
;                 }
;                 __syncthreads();
;             }
;             else { XcdBarrier xb_; xb_.bar = (unsigned*)F.ws; xb_.x = xb_xcc_id(); xb_.st = (volatile LAS unsigned*)(F.lds + 131072 + 64); xcd_barrier(xb_); if (SYNC2) xcd_barrier(xb_); }
.LBB0_790:
	s_andn2_saveexec_b64 s[8:9], s[8:9]
	s_cbranch_execz .LBB0_1139
	v_readlane_b32 s8, v255, 62
	v_readlane_b32 s9, v254, 24
	v_readlane_b32 s10, v254, 27
	s_cmp_eq_u32 s8, 0
	s_cbranch_scc1 .Lxb_global
	s_cmpk_lg_i32 s82, 0x100
	s_cbranch_scc1 .Lxb_global
	s_lshr_b32 s8, 0x6c8, s9
	s_bitcmp1_b32 s8, 0
	s_cbranch_scc1 .Lxb_local
	s_cmp_lg_u32 s9, 1
	s_cbranch_scc1 .Lxb_global
	s_cmp_lg_u32 s10, 0
	s_cbranch_scc1 .Lxb_local
